# v18 + attention: v_pk_add_f32 between MFMAs split into scalar v_sub_f32 pairs (bit-identical)
# speedup vs baseline: 1.0041x; 1.0041x over previous
.LBB0_752:
	s_waitcnt lgkmcnt(0)
	v_add_f32_e32 v11, v12, v11
	v_add_f32_e32 v11, v11, v14
	v_add_f32_e32 v11, v11, v13
	v_add_f32_e32 v11, v11, v16
	v_add_f32_e32 v11, v11, v15
	v_add_f32_e32 v11, v11, v18
	v_cndmask_b32_e64 v0, v10, v0, s[20:21]
	v_add_f32_e32 v10, v11, v17
	v_add_f32_e32 v0, v0, v10
	v_sub_f32_e32 v0, v0, v3
	v_add_f32_e32 v6, v6, v0
	v_add_f32_e32 v7, v7, v0
	v_add_f32_e32 v8, v8, v0
	v_add_f32_e32 v9, v9, v0
	s_mov_b32 s2, 0x3fb8aa3b
	v_pk_mul_f32 v[8:9], v[8:9], s[2:3] op_sel_hi:[1,0]
	v_pk_mul_f32 v[6:7], v[6:7], s[2:3] op_sel_hi:[1,0]
	ds_write_b128 v240, v[6:9]
	v_add_f32_e32 v6, v4, v0
	v_add_f32_e32 v7, v5, v0
	v_add_f32_e32 v2, v2, v0
	v_add_f32_e32 v3, v3, v0
	s_mov_b64 s[4:5], 0
	v_pk_mul_f32 v[4:5], v[2:3], s[2:3] op_sel_hi:[1,0]
	v_pk_mul_f32 v[2:3], v[6:7], s[2:3] op_sel_hi:[1,0]
	s_mov_b64 s[2:3], 0
	ds_write_b128 v240, v[2:5] offset:16
	s_waitcnt lgkmcnt(0)
	s_barrier
	s_mov_b64 s[24:25], exec
	v_readlane_b32 s8, v254, 33
	v_readlane_b32 s9, v254, 34
	s_and_b64 s[8:9], s[24:25], s[8:9]
	s_mov_b64 exec, s[8:9]
	s_cbranch_execz .LBB0_754
	v_readlane_b32 s3, v254, 16
	s_add_i32 s2, 0, 0x15000
	v_add_u32_e32 v2, s2, v232
	v_mov_b32_e32 v0, s3
	ds_read_b32 v0, v0
	ds_read_b32 v2, v2 offset:252
	s_waitcnt lgkmcnt(1)
	v_sub_f32_e32 v0, v0, v233
	v_add_f32_e32 v0, 0x42340000, v0
	s_waitcnt lgkmcnt(0)
	v_cmp_gt_f32_e32 vcc, v2, v0
	s_and_b64 s[2:3], vcc, exec

.LBB0_773:
	ds_read_b128 v[80:83], v210
	ds_read_b128 v[100:103], v210 offset:32
	ds_read_b128 v[148:151], v210 offset:128
	ds_read_b128 v[84:87], v210 offset:160
	ds_read_b128 v[104:107], v210 offset:64
	ds_read_b128 v[108:111], v210 offset:96
	ds_read_b128 v[88:91], v210 offset:192
	ds_read_b128 v[92:95], v210 offset:224
	s_waitcnt lgkmcnt(14)
	v_mfma_f32_32x32x16_bf16 v[32:47], v[140:143], v[176:179], v[32:47]
	v_exp_f32_e32 v64, v64
	v_exp_f32_e32 v65, v65
	v_exp_f32_e32 v66, v66
	v_exp_f32_e32 v67, v67
	s_waitcnt lgkmcnt(7)
	v_sub_f32_e64 v96, -v208, v80
	v_sub_f32_e64 v97, -v208, v81
	v_sub_f32_e64 v98, -v208, v82
	v_sub_f32_e64 v99, -v208, v83
	s_waitcnt lgkmcnt(2)
	v_mfma_f32_32x32x16_bf16 v[16:31], v[140:143], v[172:175], v[16:31]
	v_exp_f32_e32 v68, v68
	v_exp_f32_e32 v69, v69
	v_exp_f32_e32 v70, v70
	v_exp_f32_e32 v71, v71
	v_sub_f32_e64 v100, -v208, v100
	v_sub_f32_e64 v101, -v208, v101
	v_sub_f32_e64 v102, -v208, v102
	v_sub_f32_e64 v103, -v208, v103
	v_add_u32_e32 v0, s60, v250
	ds_read_b128 v[180:183], v0
	ds_read_b128 v[144:147], v0 offset:512
	v_mfma_f32_32x32x16_bf16 v[32:47], v[136:139], v[168:171], v[32:47]
	v_exp_f32_e32 v72, v72
	v_exp_f32_e32 v73, v73
	v_exp_f32_e32 v74, v74
	v_exp_f32_e32 v75, v75
	v_sub_f32_e64 v104, -v208, v104
	v_sub_f32_e64 v105, -v208, v105
	v_sub_f32_e64 v106, -v208, v106
	v_sub_f32_e64 v107, -v208, v107
	ds_read_b128 v[176:179], v0 offset:2048
	ds_read_b128 v[152:155], v0 offset:2560
	v_mfma_f32_32x32x16_bf16 v[16:31], v[136:139], v[164:167], v[16:31]
	v_exp_f32_e32 v76, v76
	v_exp_f32_e32 v77, v77
	v_exp_f32_e32 v78, v78
	v_exp_f32_e32 v79, v79
	v_sub_f32_e64 v108, -v208, v108
	v_sub_f32_e64 v109, -v208, v109
	v_sub_f32_e64 v110, -v208, v110
	v_sub_f32_e64 v111, -v208, v111
	ds_read_b128 v[172:175], v0 offset:4096
	ds_read_b128 v[156:159], v0 offset:4608
	v_mfma_f32_32x32x16_bf16 v[32:47], v[132:135], v[160:163], v[32:47]
	v_exp_f32_e32 v48, v48
	v_exp_f32_e32 v49, v49
	v_exp_f32_e32 v50, v50
	v_exp_f32_e32 v51, v51
	v_sub_f32_e64 v80, -v208, v148
	v_sub_f32_e64 v81, -v208, v149
	v_sub_f32_e64 v82, -v208, v150
	v_sub_f32_e64 v83, -v208, v151
	s_waitcnt lgkmcnt(6)
	ds_read_b128 v[168:171], v0 offset:6144
	ds_read_b128 v[148:151], v0 offset:6656
	v_mfma_f32_32x32x16_bf16 v[16:31], v[132:135], v[10:13], v[16:31]
	v_exp_f32_e32 v52, v52
	v_exp_f32_e32 v53, v53
	v_exp_f32_e32 v54, v54
	v_exp_f32_e32 v55, v55
	v_sub_f32_e64 v84, -v208, v84
	v_sub_f32_e64 v85, -v208, v85
	v_sub_f32_e64 v86, -v208, v86
	v_sub_f32_e64 v87, -v208, v87
	v_mfma_f32_32x32x16_bf16 v[32:47], v[128:131], v[6:9], v[32:47]
	v_exp_f32_e32 v56, v56
	v_exp_f32_e32 v57, v57
	v_exp_f32_e32 v58, v58
	v_exp_f32_e32 v59, v59
	v_sub_f32_e64 v88, -v208, v88
	v_sub_f32_e64 v89, -v208, v89
	v_sub_f32_e64 v90, -v208, v90
	v_sub_f32_e64 v91, -v208, v91
	v_mfma_f32_32x32x16_bf16 v[16:31], v[128:131], v[2:5], v[16:31]
	v_exp_f32_e32 v60, v60
	v_exp_f32_e32 v61, v61
	v_exp_f32_e32 v62, v62
	v_exp_f32_e32 v63, v63
	v_sub_f32_e64 v92, -v208, v92
	v_sub_f32_e64 v93, -v208, v93
	v_sub_f32_e64 v94, -v208, v94
	v_sub_f32_e64 v95, -v208, v95
	s_waitcnt vmcnt(2) lgkmcnt(0)
	s_barrier
	s_andn2_b64 vcc, exec, s[4:5]
	v_add_u32_e32 v0, s73, v216
	s_cbranch_vccnz .LBB0_775
	s_waitcnt lgkmcnt(0)
	ds_read_b128 v[2:5], v0 offset:49248
	ds_read_b128 v[6:9], v0 offset:49216
	ds_read_b128 v[10:13], v0 offset:49184
	ds_read_b128 v[160:163], v0 offset:49152
	s_waitcnt lgkmcnt(3)
	v_pk_mul_f32 v[44:45], v[44:45], v[2:3]
	s_waitcnt lgkmcnt(2)
	v_pk_mul_f32 v[40:41], v[40:41], v[6:7]
	s_waitcnt lgkmcnt(1)
	v_pk_mul_f32 v[36:37], v[36:37], v[10:11]
	v_pk_mul_f32 v[46:47], v[46:47], v[4:5]
	v_pk_mul_f32 v[42:43], v[42:43], v[8:9]
	v_pk_mul_f32 v[38:39], v[38:39], v[12:13]
	s_waitcnt lgkmcnt(0)
	v_pk_mul_f32 v[34:35], v[34:35], v[162:163]
	v_pk_mul_f32 v[32:33], v[32:33], v[160:161]
	v_pk_mul_f32 v[28:29], v[28:29], v[2:3]
	v_pk_mul_f32 v[24:25], v[24:25], v[6:7]
	v_pk_mul_f32 v[20:21], v[20:21], v[10:11]
	v_pk_mul_f32 v[30:31], v[30:31], v[4:5]
	v_pk_mul_f32 v[26:27], v[26:27], v[8:9]
	v_pk_mul_f32 v[22:23], v[22:23], v[12:13]
	v_pk_mul_f32 v[18:19], v[18:19], v[162:163]
	v_pk_mul_f32 v[16:17], v[16:17], v[160:161]

.LBB0_776:
	ds_read_b128 v[48:51], v210 offset:256
	ds_read_b128 v[68:71], v210 offset:288
	ds_read_b128 v[176:179], v210 offset:384
	ds_read_b128 v[52:55], v210 offset:416
	ds_read_b128 v[72:75], v210 offset:320
	ds_read_b128 v[76:79], v210 offset:352
	ds_read_b128 v[56:59], v210 offset:448
	ds_read_b128 v[60:63], v210 offset:480
	s_waitcnt lgkmcnt(14)
	v_mfma_f32_32x32x16_bf16 v[32:47], v[140:143], v[184:187], v[32:47]
	v_exp_f32_e32 v96, v96
	v_exp_f32_e32 v97, v97
	v_exp_f32_e32 v98, v98
	v_exp_f32_e32 v99, v99
	s_waitcnt lgkmcnt(7)
	v_sub_f32_e64 v64, -v208, v48
	v_sub_f32_e64 v65, -v208, v49
	v_sub_f32_e64 v66, -v208, v50
	v_sub_f32_e64 v67, -v208, v51
	s_waitcnt lgkmcnt(2)
	v_mfma_f32_32x32x16_bf16 v[16:31], v[140:143], v[164:167], v[16:31]
	v_exp_f32_e32 v100, v100
	v_exp_f32_e32 v101, v101
	v_exp_f32_e32 v102, v102
	v_exp_f32_e32 v103, v103
	v_sub_f32_e64 v68, -v208, v68
	v_sub_f32_e64 v69, -v208, v69
	v_sub_f32_e64 v70, -v208, v70
	v_sub_f32_e64 v71, -v208, v71
	v_add_u32_e32 v14, s65, v250
	ds_read_b128 v[172:175], v14
	ds_read_b128 v[168:171], v14 offset:512
	v_mfma_f32_32x32x16_bf16 v[32:47], v[136:139], v[160:163], v[32:47]
	v_exp_f32_e32 v104, v104
	v_exp_f32_e32 v105, v105
	v_exp_f32_e32 v106, v106
	v_exp_f32_e32 v107, v107
	v_sub_f32_e64 v72, -v208, v72
	v_sub_f32_e64 v73, -v208, v73
	v_sub_f32_e64 v74, -v208, v74
	v_sub_f32_e64 v75, -v208, v75
	ds_read_b128 v[164:167], v14 offset:2048
	ds_read_b128 v[160:163], v14 offset:2560
	v_mfma_f32_32x32x16_bf16 v[16:31], v[136:139], v[144:147], v[16:31]
	v_exp_f32_e32 v108, v108
	v_exp_f32_e32 v109, v109
	v_exp_f32_e32 v110, v110
	v_exp_f32_e32 v111, v111
	v_sub_f32_e64 v76, -v208, v76
	v_sub_f32_e64 v77, -v208, v77
	v_sub_f32_e64 v78, -v208, v78
	v_sub_f32_e64 v79, -v208, v79
	ds_read_b128 v[156:159], v14 offset:4096
	ds_read_b128 v[148:151], v14 offset:4608
	v_mfma_f32_32x32x16_bf16 v[32:47], v[132:135], v[152:155], v[32:47]
	v_exp_f32_e32 v80, v80
	v_exp_f32_e32 v81, v81
	v_exp_f32_e32 v82, v82
	v_exp_f32_e32 v83, v83
	v_sub_f32_e64 v48, -v208, v176
	v_sub_f32_e64 v49, -v208, v177
	v_sub_f32_e64 v50, -v208, v178
	v_sub_f32_e64 v51, -v208, v179
	s_waitcnt lgkmcnt(6)
	ds_read_b128 v[152:155], v14 offset:6144
	ds_read_b128 v[144:147], v14 offset:6656
	v_mfma_f32_32x32x16_bf16 v[16:31], v[132:135], v[10:13], v[16:31]
	v_exp_f32_e32 v84, v84
	v_exp_f32_e32 v85, v85
	v_exp_f32_e32 v86, v86
	v_exp_f32_e32 v87, v87
	v_sub_f32_e64 v52, -v208, v52
	v_sub_f32_e64 v53, -v208, v53
	v_sub_f32_e64 v54, -v208, v54
	v_sub_f32_e64 v55, -v208, v55
	v_mfma_f32_32x32x16_bf16 v[32:47], v[128:131], v[6:9], v[32:47]
	v_exp_f32_e32 v88, v88
	v_exp_f32_e32 v89, v89
	v_exp_f32_e32 v90, v90
	v_exp_f32_e32 v91, v91
	v_sub_f32_e64 v56, -v208, v56
	v_sub_f32_e64 v57, -v208, v57
	v_sub_f32_e64 v58, -v208, v58
	v_sub_f32_e64 v59, -v208, v59
	v_mfma_f32_32x32x16_bf16 v[16:31], v[128:131], v[2:5], v[16:31]
	v_exp_f32_e32 v92, v92
	v_exp_f32_e32 v93, v93
	v_exp_f32_e32 v94, v94
	v_exp_f32_e32 v95, v95
	v_sub_f32_e64 v60, -v208, v60
	v_sub_f32_e64 v61, -v208, v61
	v_sub_f32_e64 v62, -v208, v62
	v_sub_f32_e64 v63, -v208, v63
	s_waitcnt vmcnt(2) lgkmcnt(0)
	s_barrier
	s_andn2_b64 vcc, exec, s[4:5]
	s_cbranch_vccnz .LBB0_778
	s_waitcnt lgkmcnt(0)
	ds_read_b128 v[2:5], v0 offset:49248
	ds_read_b128 v[6:9], v0 offset:49216
	ds_read_b128 v[10:13], v0 offset:49184
	ds_read_b128 v[176:179], v0 offset:49152
	s_waitcnt lgkmcnt(3)
	v_pk_mul_f32 v[44:45], v[44:45], v[2:3]
	s_waitcnt lgkmcnt(2)
	v_pk_mul_f32 v[40:41], v[40:41], v[6:7]
	s_waitcnt lgkmcnt(1)
	v_pk_mul_f32 v[36:37], v[36:37], v[10:11]
	v_pk_mul_f32 v[46:47], v[46:47], v[4:5]
	v_pk_mul_f32 v[42:43], v[42:43], v[8:9]
	v_pk_mul_f32 v[38:39], v[38:39], v[12:13]
	s_waitcnt lgkmcnt(0)
	v_pk_mul_f32 v[34:35], v[34:35], v[178:179]
	v_pk_mul_f32 v[32:33], v[32:33], v[176:177]
	v_pk_mul_f32 v[28:29], v[28:29], v[2:3]
	v_pk_mul_f32 v[24:25], v[24:25], v[6:7]
	v_pk_mul_f32 v[20:21], v[20:21], v[10:11]
	v_pk_mul_f32 v[30:31], v[30:31], v[4:5]
	v_pk_mul_f32 v[26:27], v[26:27], v[8:9]
	v_pk_mul_f32 v[22:23], v[22:23], v[12:13]
	v_pk_mul_f32 v[18:19], v[18:19], v[178:179]
	v_pk_mul_f32 v[16:17], v[16:17], v[176:177]

.LBB0_804:
	ds_read_b128 v[80:83], v0
	ds_read_b128 v[100:103], v0 offset:32
	ds_read_b128 v[144:147], v0 offset:128
	ds_read_b128 v[84:87], v0 offset:160
	ds_read_b128 v[104:107], v0 offset:64
	ds_read_b128 v[108:111], v0 offset:96
	ds_read_b128 v[88:91], v0 offset:192
	ds_read_b128 v[92:95], v0 offset:224
	s_waitcnt lgkmcnt(14)
	v_mfma_f32_32x32x16_bf16 v[32:47], v[140:143], v[188:191], v[32:47]
	v_exp_f32_e32 v64, v64
	v_exp_f32_e32 v65, v65
	v_exp_f32_e32 v66, v66
	v_exp_f32_e32 v67, v67
	s_waitcnt lgkmcnt(7)
	v_sub_f32_e64 v96, -v208, v80
	v_sub_f32_e64 v97, -v208, v81
	v_sub_f32_e64 v98, -v208, v82
	v_sub_f32_e64 v99, -v208, v83
	s_waitcnt lgkmcnt(2)
	v_mfma_f32_32x32x16_bf16 v[16:31], v[140:143], v[172:175], v[16:31]
	v_exp_f32_e32 v68, v68
	v_exp_f32_e32 v69, v69
	v_exp_f32_e32 v70, v70
	v_exp_f32_e32 v71, v71
	v_sub_f32_e64 v100, -v208, v100
	v_sub_f32_e64 v101, -v208, v101
	v_sub_f32_e64 v102, -v208, v102
	v_sub_f32_e64 v103, -v208, v103
	v_add_u32_e32 v140, s6, v250
	ds_read_b128 v[172:175], v140
	ds_read_b128 v[168:171], v140 offset:512
	v_mfma_f32_32x32x16_bf16 v[32:47], v[136:139], v[184:187], v[32:47]
	v_exp_f32_e32 v72, v72
	v_exp_f32_e32 v73, v73
	v_exp_f32_e32 v74, v74
	v_exp_f32_e32 v75, v75
	v_sub_f32_e64 v104, -v208, v104
	v_sub_f32_e64 v105, -v208, v105
	v_sub_f32_e64 v106, -v208, v106
	v_sub_f32_e64 v107, -v208, v107
	ds_read_b128 v[164:167], v140 offset:2048
	ds_read_b128 v[160:163], v140 offset:2560
	v_mfma_f32_32x32x16_bf16 v[16:31], v[136:139], v[176:179], v[16:31]
	v_exp_f32_e32 v76, v76
	v_exp_f32_e32 v77, v77
	v_exp_f32_e32 v78, v78
	v_exp_f32_e32 v79, v79
	v_sub_f32_e64 v108, -v208, v108
	v_sub_f32_e64 v109, -v208, v109
	v_sub_f32_e64 v110, -v208, v110
	v_sub_f32_e64 v111, -v208, v111
	ds_read_b128 v[156:159], v140 offset:4096
	ds_read_b128 v[148:151], v140 offset:4608
	v_mfma_f32_32x32x16_bf16 v[32:47], v[132:135], v[180:183], v[32:47]
	v_exp_f32_e32 v48, v48
	v_exp_f32_e32 v49, v49
	v_exp_f32_e32 v50, v50
	v_exp_f32_e32 v51, v51
	v_sub_f32_e64 v80, -v208, v144
	v_sub_f32_e64 v81, -v208, v145
	v_sub_f32_e64 v82, -v208, v146
	v_sub_f32_e64 v83, -v208, v147
	s_waitcnt lgkmcnt(6)
	ds_read_b128 v[152:155], v140 offset:6144
	ds_read_b128 v[144:147], v140 offset:6656
	v_mfma_f32_32x32x16_bf16 v[16:31], v[132:135], v[10:13], v[16:31]
	v_exp_f32_e32 v52, v52
	v_exp_f32_e32 v53, v53
	v_exp_f32_e32 v54, v54
	v_exp_f32_e32 v55, v55
	v_sub_f32_e64 v84, -v208, v84
	v_sub_f32_e64 v85, -v208, v85
	v_sub_f32_e64 v86, -v208, v86
	v_sub_f32_e64 v87, -v208, v87
	v_mfma_f32_32x32x16_bf16 v[32:47], v[128:131], v[6:9], v[32:47]
	v_exp_f32_e32 v56, v56
	v_exp_f32_e32 v57, v57
	v_exp_f32_e32 v58, v58
	v_exp_f32_e32 v59, v59
	v_sub_f32_e64 v88, -v208, v88
	v_sub_f32_e64 v89, -v208, v89
	v_sub_f32_e64 v90, -v208, v90
	v_sub_f32_e64 v91, -v208, v91
	v_mfma_f32_32x32x16_bf16 v[16:31], v[128:131], v[2:5], v[16:31]
	v_exp_f32_e32 v60, v60
	v_exp_f32_e32 v61, v61
	v_exp_f32_e32 v62, v62
	v_exp_f32_e32 v63, v63
	v_sub_f32_e64 v92, -v208, v92
	v_sub_f32_e64 v93, -v208, v93
	v_sub_f32_e64 v94, -v208, v94
	v_sub_f32_e64 v95, -v208, v95
	s_mov_b64 s[24:25], -1
	s_and_b64 vcc, exec, s[2:3]
	s_cbranch_vccz .LBB0_855
	s_cmp_ge_i32 s88, s7
	s_cbranch_scc0 .LBB0_807
	s_waitcnt vmcnt(0) lgkmcnt(0)
	s_barrier
	s_mov_b64 s[24:25], 0

.LBB0_821:
	s_waitcnt lgkmcnt(14)
	v_mfma_f32_32x32x16_bf16 v[32:47], v[140:143], v[192:195], v[32:47]
	v_exp_f32_e32 v96, v96
	v_exp_f32_e32 v97, v97
	v_exp_f32_e32 v98, v98
	v_exp_f32_e32 v99, v99
	s_and_b64 vcc, exec, s[24:25]
	s_cbranch_vccnz .LBB0_823
	s_waitcnt lgkmcnt(7)
	v_sub_f32_e64 v65, -v208, v65
	v_sub_f32_e64 v64, -v208, v64
	v_sub_f32_e64 v66, -v208, v66
	v_sub_f32_e64 v67, -v208, v67
	s_waitcnt lgkmcnt(2)
.LBB0_823:
	s_waitcnt lgkmcnt(12)
	v_mfma_f32_32x32x16_bf16 v[16:31], v[140:143], v[188:191], v[16:31]
	v_exp_f32_e32 v100, v100
	v_exp_f32_e32 v101, v101
	v_exp_f32_e32 v102, v102
	v_exp_f32_e32 v103, v103
	s_and_b64 vcc, exec, s[24:25]
	s_cbranch_vccnz .LBB0_825
	s_waitcnt lgkmcnt(6)
	v_sub_f32_e64 v68, -v208, v68
	v_sub_f32_e64 v69, -v208, v69
	v_sub_f32_e64 v70, -v208, v70
	v_sub_f32_e64 v71, -v208, v71
	s_waitcnt lgkmcnt(2)

.LBB0_827:
	s_waitcnt lgkmcnt(10)
	v_mfma_f32_32x32x16_bf16 v[32:47], v[136:139], v[184:187], v[32:47]
	v_exp_f32_e32 v104, v104
	v_exp_f32_e32 v105, v105
	v_exp_f32_e32 v106, v106
	v_exp_f32_e32 v107, v107
	s_and_b64 vcc, exec, s[24:25]
	s_cbranch_vccnz .LBB0_829
	s_waitcnt lgkmcnt(3)
	v_sub_f32_e64 v72, -v208, v72
	v_sub_f32_e64 v73, -v208, v73
	v_sub_f32_e64 v74, -v208, v74
	v_sub_f32_e64 v75, -v208, v75
	s_waitcnt lgkmcnt(2)

.LBB0_831:
	s_waitcnt lgkmcnt(8)
	v_mfma_f32_32x32x16_bf16 v[16:31], v[136:139], v[180:183], v[16:31]
	v_exp_f32_e32 v108, v108
	v_exp_f32_e32 v109, v109
	v_exp_f32_e32 v110, v110
	v_exp_f32_e32 v111, v111
	s_and_b64 vcc, exec, s[24:25]
	s_cbranch_vccnz .LBB0_833
	s_waitcnt lgkmcnt(2)
	v_sub_f32_e64 v76, -v208, v76
	v_sub_f32_e64 v77, -v208, v77
	v_sub_f32_e64 v78, -v208, v78
	v_sub_f32_e64 v79, -v208, v79

.LBB0_835:
	s_waitcnt lgkmcnt(6)
	v_mfma_f32_32x32x16_bf16 v[32:47], v[132:135], v[176:179], v[32:47]
	v_exp_f32_e32 v80, v80
	v_exp_f32_e32 v81, v81
	v_exp_f32_e32 v82, v82
	v_exp_f32_e32 v83, v83
	s_and_b64 vcc, exec, s[24:25]
	s_cbranch_vccnz .LBB0_837
	s_waitcnt lgkmcnt(5)
	v_sub_f32_e64 v49, -v208, v49
	v_sub_f32_e64 v48, -v208, v48
	v_sub_f32_e64 v50, -v208, v50
	v_sub_f32_e64 v51, -v208, v51
	s_waitcnt lgkmcnt(0)

.LBB0_839:
	s_waitcnt lgkmcnt(4)
	v_mfma_f32_32x32x16_bf16 v[16:31], v[132:135], v[10:13], v[16:31]
	v_exp_f32_e32 v84, v84
	v_exp_f32_e32 v85, v85
	v_exp_f32_e32 v86, v86
	v_exp_f32_e32 v87, v87
	s_and_b64 vcc, exec, s[24:25]
	s_cbranch_vccnz .LBB0_841
	v_sub_f32_e64 v52, -v208, v52
	v_sub_f32_e64 v53, -v208, v53
	v_sub_f32_e64 v54, -v208, v54
	v_sub_f32_e64 v55, -v208, v55
	s_waitcnt lgkmcnt(0)
.LBB0_841:
	s_waitcnt lgkmcnt(2)
	v_mfma_f32_32x32x16_bf16 v[32:47], v[128:131], v[6:9], v[32:47]
	v_exp_f32_e32 v88, v88
	v_exp_f32_e32 v89, v89
	v_exp_f32_e32 v90, v90
	v_exp_f32_e32 v91, v91
	s_and_b64 vcc, exec, s[24:25]
	s_cbranch_vccnz .LBB0_843
	s_waitcnt lgkmcnt(1)
	v_sub_f32_e64 v56, -v208, v56
	v_sub_f32_e64 v57, -v208, v57
	v_sub_f32_e64 v58, -v208, v58
	v_sub_f32_e64 v59, -v208, v59
	s_waitcnt lgkmcnt(0)
.LBB0_843:
	s_waitcnt lgkmcnt(0)
	v_mfma_f32_32x32x16_bf16 v[16:31], v[128:131], v[2:5], v[16:31]
	v_exp_f32_e32 v92, v92
	v_exp_f32_e32 v93, v93
	v_exp_f32_e32 v94, v94
	v_exp_f32_e32 v95, v95
	s_and_b64 vcc, exec, s[24:25]
	s_cbranch_vccnz .LBB0_845
	v_sub_f32_e64 v60, -v208, v60
	v_sub_f32_e64 v61, -v208, v61
	v_sub_f32_e64 v62, -v208, v62
	v_sub_f32_e64 v63, -v208, v63
